# phase-0 grid barrier: 8 sharded arrival counters + top counter in the zeroed workspace barrier words instead of the single-counter cooperative-groups barrier
# speedup vs baseline: 1.0346x; 1.0026x over previous
; __global__ void __launch_bounds__(256, 2) mega_fwd(Params p) {
;     ...
;     grid.sync();
.LBB0_181:
	v_lshrrev_b32_e32 v1, 20, v0
	v_lshrrev_b32_e32 v0, 10, v0
	v_or_b32_e32 v0, v0, v1
	s_movk_i32 s0, 0x3ff
	v_and_or_b32 v0, v0, s0, v197
	v_cmp_eq_u32_e32 vcc, 0, v0
	s_waitcnt lgkmcnt(0)
	s_barrier
	s_and_saveexec_b64 s[0:1], vcc
	s_xor_b64 s[0:1], exec, s[0:1]
	s_cbranch_execz .LBB0_191
	buffer_wbl2 sc1
	s_waitcnt vmcnt(0)
	s_load_dword s4, s[12:13], 0x0
	v_readlane_b32 s5, v251, 0
	s_and_b32 s8, s5, 7
	s_lshl_b32 s9, s8, 8
	s_add_u32 s10, s80, 0x1c0db100
	s_addc_u32 s11, s81, 0
	s_add_u32 s10, s10, 0x3700
	s_addc_u32 s11, s11, 0
	v_mov_b32_e32 v0, s9
	v_mov_b32_e32 v1, 1
	global_atomic_add v2, v0, v1, s[10:11] sc0
	s_waitcnt lgkmcnt(0)
	s_add_i32 s4, s4, 7
	s_sub_i32 s4, s4, s8
	s_lshr_b32 s4, s4, 3
	s_add_i32 s4, s4, -1
	s_waitcnt vmcnt(0)
	v_cmp_eq_u32_e32 vcc, s4, v2
	v_mov_b32_e32 v0, 0x800
	s_and_saveexec_b64 s[8:9], vcc
	s_cbranch_execz .Lgb_na
	global_atomic_add v0, v1, s[10:11]

; __global__ void __launch_bounds__(256, 2) mega_fwd(Params p) {
;     ...
;     grid.sync();
.Lgb_spin:
	s_sleep 1
	global_load_dword v2, v0, s[10:11] sc1
	s_waitcnt vmcnt(0)
	v_cmp_gt_u32_e32 vcc, 8, v2
	s_cbranch_vccnz .Lgb_spin
	buffer_inv sc1
